# grid barrier: top arrival counter replicated per XCD (leaders add to all copies, each XCD polls its own copy)
# speedup vs baseline: 1.0201x; 1.0048x over previous
; __device__ __forceinline__ unsigned xb_ld(unsigned* p)              { return __hip_atomic_load(p, __ATOMIC_RELAXED, __HIP_MEMORY_SCOPE_AGENT); }
; __device__ __forceinline__ unsigned xb_add(unsigned* p, unsigned v) { return __hip_atomic_fetch_add(p, v, __ATOMIC_RELAXED, __HIP_MEMORY_SCOPE_AGENT); }
; #define XB_SPIN(cond, bar) do { unsigned _sp = 0; while (cond) { __builtin_amdgcn_s_sleep(1); \
;     if ((++_sp & 255u) == 0u) { if (xb_ld(&(bar)[XB_TMO])) break; if (_sp > XB_SPIN_CAP) { atomicAdd(&(bar)[XB_TMO], 1u); break; } } } } while (0)
; __device__ __forceinline__ void xcd_barrier(const XcdBarrier& b) {
;     ...
;         const unsigned old = xb_add(&bar[XB_XSUB(b.x)], 1u);
;         const unsigned gen = old / nloc;
;         if (old + 1u == (gen + 1u) * nloc) {
;             __builtin_amdgcn_fence(__ATOMIC_RELEASE, "agent");
;             asm volatile("s_waitcnt vmcnt(0)" ::: "memory");
;             const unsigned og = xb_add(&bar[XB_TOP], 1u);
;             const unsigned tg = og / nx;
;             if (og + 1u == (tg + 1u) * nx) xb_add(&bar[XB_TOPGEN], 1u);
;             else XB_SPIN(xb_ld(&bar[XB_TOPGEN]) == tg, bar);
;             __builtin_amdgcn_fence(__ATOMIC_ACQUIRE, "agent");
;             xb_add(&bar[XB_XGEN(b.x)], 1u);
;             asm volatile("s_waitcnt vmcnt(0)" ::: "memory");
;         } else {
;             XB_SPIN(xb_ld(&bar[XB_XGEN(b.x)]) == gen, bar);
;             __builtin_amdgcn_fence(__ATOMIC_ACQUIRE, "agent");
;             asm volatile("s_waitcnt vmcnt(0)" ::: "memory");
;         }
.LBB0_282:
	s_or_b64 exec, exec, s[10:11]
	v_cvt_f32_u32_e32 v6, v4
	s_waitcnt vmcnt(0)
	v_readfirstlane_b32 s3, v5
	v_sub_u32_e32 v5, 0, v4
	v_rcp_iflag_f32_e32 v6, v6
	v_add_u32_e32 v7, s3, v3
	v_mul_f32_e32 v6, 0x4f7ffffe, v6
	v_cvt_u32_f32_e32 v6, v6
	v_mul_lo_u32 v3, v5, v6
	v_mul_hi_u32 v3, v6, v3
	v_add_u32_e32 v3, v6, v3
	v_mul_hi_u32 v3, v7, v3
	v_mul_lo_u32 v5, v3, v4
	v_sub_u32_e32 v5, v7, v5
	v_add_u32_e32 v6, 1, v3
	v_cmp_ge_u32_e32 vcc, v5, v4
	s_nop 1
	v_cndmask_b32_e32 v3, v3, v6, vcc
	v_sub_u32_e32 v6, v5, v4
	v_cndmask_b32_e32 v5, v5, v6, vcc
	v_add_u32_e32 v6, 1, v3
	v_cmp_ge_u32_e32 vcc, v5, v4
	v_add_u32_e32 v5, 1, v7
	s_nop 0
	v_cndmask_b32_e32 v3, v3, v6, vcc
	v_mul_lo_u32 v6, v4, v3
	v_add_u32_e32 v4, v6, v4
	v_cmp_ne_u32_e32 vcc, v5, v4
	s_waitcnt lgkmcnt(0)
	v_mul_lo_u32 v3, v3, v2
	s_cbranch_vccnz .Lgb1_poll
	buffer_wbl2 sc1
	s_waitcnt vmcnt(0)
	v_mov_b32_e32 v4, 0x2400
	v_mov_b32_e32 v5, 1
	global_atomic_add v4, v5, s[66:67] offset:4
	global_atomic_add v4, v5, s[66:67] offset:260
	global_atomic_add v4, v5, s[66:67] offset:516
	global_atomic_add v4, v5, s[66:67] offset:772
	global_atomic_add v4, v5, s[66:67] offset:1028
	global_atomic_add v4, v5, s[66:67] offset:1284
	global_atomic_add v4, v5, s[66:67] offset:1540
	global_atomic_add v4, v5, s[66:67] offset:1796
	global_atomic_add v4, v5, s[66:67] offset:2052
	global_atomic_add v4, v5, s[66:67] offset:2308
	global_atomic_add v4, v5, s[66:67] offset:2564
	global_atomic_add v4, v5, s[66:67] offset:2820
	global_atomic_add v4, v5, s[66:67] offset:3076
	global_atomic_add v4, v5, s[66:67] offset:3332
	global_atomic_add v4, v5, s[66:67] offset:3588
	global_atomic_add v4, v5, s[66:67] offset:3844
.Lgb1_poll:
	v_mov_b32_e32 v4, 0x2000
	s_mov_b32 s3, 0
.Lgb1_loop:
	global_load_dword v5, v4, s[6:7] offset:1028 sc1
	s_add_u32 s3, s3, 1
	s_waitcnt vmcnt(0)
	v_cmp_ge_u32_e32 vcc, v5, v3
	s_cbranch_vccnz .Lgb1_done
	s_cmp_lt_u32 s3, 0x40000
	s_cbranch_scc0 .Lgb1_done
	s_sleep 1
	s_branch .Lgb1_loop
